# context split-K slab stores (f32 partial slabs read by ctx_norm after the grid barrier) write-through (sc1)
# speedup vs baseline: 1.0084x; 1.0019x over previous
.LBB0_827:
	v_lshl_or_b32 v136, s23, 8, v134
	s_ashr_i32 s23, s22, 31
	s_lshl_b64 s[22:23], s[22:23], 22
	s_add_u32 s22, s44, s22
	v_lshl_add_u32 v138, s37, 8, v132
	s_addc_u32 s23, s45, s23
	v_ashrrev_i32_e32 v137, 31, v136
	v_ashrrev_i32_e32 v139, 31, v138
	v_lshl_add_u64 v[136:137], v[136:137], 2, s[22:23]
	v_lshlrev_b64 v[140:141], 12, v[138:139]
	v_lshl_add_u64 v[140:141], v[136:137], 0, v[140:141]
	flat_store_dwordx4 v[140:141], v[34:37] sc1
	flat_store_dwordx4 v[140:141], v[38:41] offset:64 sc1
	flat_store_dwordx4 v[140:141], v[70:73] offset:512 sc1
	flat_store_dwordx4 v[140:141], v[78:81] offset:576 sc1
	v_or_b32_e32 v34, 16, v138
	v_ashrrev_i32_e32 v35, 31, v34
	v_lshlrev_b64 v[34:35], 12, v[34:35]
	v_lshl_add_u64 v[34:35], v[136:137], 0, v[34:35]
	flat_store_dwordx4 v[34:35], v[18:21] sc1
	flat_store_dwordx4 v[34:35], v[22:25] offset:64 sc1
	flat_store_dwordx4 v[34:35], v[58:61] offset:512 sc1
	flat_store_dwordx4 v[34:35], v[62:65] offset:576 sc1
	v_or_b32_e32 v18, 32, v138
	v_ashrrev_i32_e32 v19, 31, v18
	v_lshlrev_b64 v[18:19], 12, v[18:19]
	v_lshl_add_u64 v[18:19], v[136:137], 0, v[18:19]
	flat_store_dwordx4 v[18:19], v[10:13] sc1
	flat_store_dwordx4 v[18:19], v[14:17] offset:64 sc1
	flat_store_dwordx4 v[18:19], v[42:45] offset:512 sc1
	flat_store_dwordx4 v[18:19], v[46:49] offset:576 sc1
	v_or_b32_e32 v10, 48, v138
	v_ashrrev_i32_e32 v11, 31, v10
	v_lshlrev_b64 v[10:11], 12, v[10:11]
	v_lshl_add_u64 v[10:11], v[136:137], 0, v[10:11]
	s_mov_b32 s15, 0x80000
	flat_store_dwordx4 v[10:11], v[2:5] sc1
	flat_store_dwordx4 v[10:11], v[6:9] offset:64 sc1
	flat_store_dwordx4 v[10:11], v[26:29] offset:512 sc1
	flat_store_dwordx4 v[10:11], v[30:33] offset:576 sc1
	v_add_co_u32_e32 v4, vcc, s15, v140
	s_mov_b64 s[22:23], 0x80000
	s_nop 0
	v_addc_co_u32_e32 v5, vcc, 0, v141, vcc
	s_mov_b32 s15, 0x90000
	v_lshl_add_u64 v[2:3], v[140:141], 0, s[22:23]
	flat_store_dwordx4 v[4:5], v[98:101] sc1
	flat_store_dwordx4 v[2:3], v[106:109] offset:64 sc1
	flat_store_dwordx4 v[2:3], v[122:125] offset:512 sc1
	flat_store_dwordx4 v[2:3], v[126:129] offset:576 sc1
	v_add_co_u32_e32 v4, vcc, s15, v140
	s_mov_b64 s[22:23], 0x90000
	s_nop 0
	v_addc_co_u32_e32 v5, vcc, 0, v141, vcc
	s_mov_b32 s15, 0xa0000
	v_lshl_add_u64 v[2:3], v[140:141], 0, s[22:23]
	flat_store_dwordx4 v[4:5], v[86:89] sc1
	flat_store_dwordx4 v[2:3], v[94:97] offset:64 sc1
	flat_store_dwordx4 v[2:3], v[114:117] offset:512 sc1
	flat_store_dwordx4 v[2:3], v[118:121] offset:576 sc1
	v_add_co_u32_e32 v4, vcc, s15, v140
	s_mov_b64 s[22:23], 0xa0000
	s_nop 0
	v_addc_co_u32_e32 v5, vcc, 0, v141, vcc
	v_lshl_add_u64 v[2:3], v[140:141], 0, s[22:23]
	flat_store_dwordx4 v[4:5], v[66:69] sc1
	flat_store_dwordx4 v[2:3], v[74:77] offset:64 sc1
	flat_store_dwordx4 v[2:3], v[102:105] offset:512 sc1
	flat_store_dwordx4 v[2:3], v[110:113] offset:576 sc1
	v_add_co_u32_e32 v4, vcc, 0xb0000, v140
	v_readlane_b32 s80, v254, 49
	s_nop 0
	v_addc_co_u32_e32 v5, vcc, 0, v141, vcc
	s_mov_b64 s[22:23], 0xb0000
	s_and_b64 vcc, exec, s[8:9]
	s_mov_b64 s[8:9], -1
	s_mov_b32 s71, 0x400000
	v_readlane_b32 s81, v254, 50
	v_lshl_add_u64 v[2:3], v[140:141], 0, s[22:23]
	flat_store_dwordx4 v[4:5], v[50:53] sc1
	flat_store_dwordx4 v[2:3], v[54:57] offset:64 sc1
	flat_store_dwordx4 v[2:3], v[82:85] offset:512 sc1
	flat_store_dwordx4 v[2:3], v[90:93] offset:576 sc1
	s_cbranch_vccnz .LBB0_818
	s_andn2_b64 vcc, exec, s[10:11]
	s_cbranch_vccnz .LBB0_817
	s_barrier
	s_branch .LBB0_817

.LBB0_1110:
	v_lshl_or_b32 v136, s17, 8, v134
	s_ashr_i32 s17, s16, 31
	s_lshl_b64 s[16:17], s[16:17], 22
	s_add_u32 s16, s44, s16
	v_lshl_add_u32 v138, s35, 8, v132
	s_addc_u32 s17, s45, s17
	v_ashrrev_i32_e32 v137, 31, v136
	v_ashrrev_i32_e32 v139, 31, v138
	v_lshl_add_u64 v[136:137], v[136:137], 2, s[16:17]
	v_lshlrev_b64 v[140:141], 12, v[138:139]
	v_lshl_add_u64 v[140:141], v[136:137], 0, v[140:141]
	flat_store_dwordx4 v[140:141], v[34:37] sc1
	flat_store_dwordx4 v[140:141], v[38:41] offset:64 sc1
	flat_store_dwordx4 v[140:141], v[70:73] offset:512 sc1
	flat_store_dwordx4 v[140:141], v[78:81] offset:576 sc1
	v_or_b32_e32 v34, 16, v138
	v_ashrrev_i32_e32 v35, 31, v34
	v_lshlrev_b64 v[34:35], 12, v[34:35]
	v_lshl_add_u64 v[34:35], v[136:137], 0, v[34:35]
	flat_store_dwordx4 v[34:35], v[18:21] sc1
	flat_store_dwordx4 v[34:35], v[22:25] offset:64 sc1
	flat_store_dwordx4 v[34:35], v[58:61] offset:512 sc1
	flat_store_dwordx4 v[34:35], v[62:65] offset:576 sc1
	v_or_b32_e32 v18, 32, v138
	v_ashrrev_i32_e32 v19, 31, v18
	v_lshlrev_b64 v[18:19], 12, v[18:19]
	v_lshl_add_u64 v[18:19], v[136:137], 0, v[18:19]
	flat_store_dwordx4 v[18:19], v[10:13] sc1
	flat_store_dwordx4 v[18:19], v[14:17] offset:64 sc1
	flat_store_dwordx4 v[18:19], v[42:45] offset:512 sc1
	flat_store_dwordx4 v[18:19], v[46:49] offset:576 sc1
	v_or_b32_e32 v10, 48, v138
	v_ashrrev_i32_e32 v11, 31, v10
	v_lshlrev_b64 v[10:11], 12, v[10:11]
	v_lshl_add_u64 v[10:11], v[136:137], 0, v[10:11]
	s_mov_b64 s[16:17], 0x80000
	flat_store_dwordx4 v[10:11], v[2:5] sc1
	flat_store_dwordx4 v[10:11], v[6:9] offset:64 sc1
	flat_store_dwordx4 v[10:11], v[26:29] offset:512 sc1
	flat_store_dwordx4 v[10:11], v[30:33] offset:576 sc1
	v_lshl_add_u64 v[2:3], v[140:141], 0, s[16:17]
	s_mov_b32 s16, 0x80000
	v_add_co_u32_e32 v4, vcc, s16, v140
	s_mov_b64 s[16:17], 0x90000
	s_nop 0
	v_addc_co_u32_e32 v5, vcc, 0, v141, vcc
	flat_store_dwordx4 v[4:5], v[98:101] sc1
	flat_store_dwordx4 v[2:3], v[106:109] offset:64 sc1
	flat_store_dwordx4 v[2:3], v[122:125] offset:512 sc1
	flat_store_dwordx4 v[2:3], v[126:129] offset:576 sc1
	v_lshl_add_u64 v[2:3], v[140:141], 0, s[16:17]
	s_mov_b32 s16, 0x90000
	v_add_co_u32_e32 v4, vcc, s16, v140
	s_mov_b64 s[16:17], 0xa0000
	s_nop 0
	v_addc_co_u32_e32 v5, vcc, 0, v141, vcc
	flat_store_dwordx4 v[4:5], v[86:89] sc1
	flat_store_dwordx4 v[2:3], v[94:97] offset:64 sc1
	flat_store_dwordx4 v[2:3], v[114:117] offset:512 sc1
	flat_store_dwordx4 v[2:3], v[118:121] offset:576 sc1
	v_lshl_add_u64 v[2:3], v[140:141], 0, s[16:17]
	s_mov_b32 s16, 0xa0000
	v_add_co_u32_e32 v4, vcc, s16, v140
	v_readlane_b32 s78, v252, 4
	s_nop 0
	v_addc_co_u32_e32 v5, vcc, 0, v141, vcc
	flat_store_dwordx4 v[4:5], v[66:69] sc1
	flat_store_dwordx4 v[2:3], v[74:77] offset:64 sc1
	flat_store_dwordx4 v[2:3], v[102:105] offset:512 sc1
	flat_store_dwordx4 v[2:3], v[110:113] offset:576 sc1
	v_add_co_u32_e32 v4, vcc, 0xb0000, v140
	v_readlane_b32 s80, v254, 49
	s_nop 0
	v_addc_co_u32_e32 v5, vcc, 0, v141, vcc
	s_mov_b64 s[16:17], 0xb0000
	s_and_b64 vcc, exec, s[6:7]
	s_mov_b64 s[6:7], -1
	v_readlane_b32 s79, v252, 5
	s_mov_b32 s71, 0x400000
	v_readlane_b32 s81, v254, 50
	v_lshl_add_u64 v[2:3], v[140:141], 0, s[16:17]
	flat_store_dwordx4 v[4:5], v[50:53] sc1
	flat_store_dwordx4 v[2:3], v[54:57] offset:64 sc1
	flat_store_dwordx4 v[2:3], v[82:85] offset:512 sc1
	flat_store_dwordx4 v[2:3], v[90:93] offset:576 sc1
	s_cbranch_vccnz .LBB0_1101
	s_andn2_b64 vcc, exec, s[8:9]
	s_cbranch_vccnz .LBB0_1100
	s_barrier
	s_branch .LBB0_1100
